# ssd_scan sample rows: each step's dt/B/C/x loads prefetched one step ahead into spare VGPRs (no per-step wait chain)
# speedup vs baseline: 1.0126x; 1.0126x over previous
; DI float bflo(unsigned w) { return __uint_as_float(w << 16); }
; DI float bfhi(unsigned w) { return __uint_as_float(w & 0xffff0000u); }
; DI float bf2f(bf16_t b) { return __uint_as_float(((unsigned)b) << 16); }
; DI void ssd_scan(const Params& P, LAS unsigned char* lds) {
;     ...
;       for (int it = gw; it < 4096; it += NW) { const int b = it >> 5, h = it & 31, g = h >> 3;
;           const float a = -__expf(P.in[I_SSMALOG][h]); const float dsk = P.in[I_SSMD][h];
;           const float* S0 = P.in[I_SSSM] + ((size_t)(b * 32 + h) * 64) * 128 + n4; float* SO = P.out + OUT_SSMS + ((size_t)(b * 32 + h) * 64) * 128 + n4;
; #pragma unroll
;           for (int half = 0; half < 2; ++half) { f32x4 S[16];
; #pragma unroll
;               for (int i = 0; i < 16; ++i) S[i] = *(const f32x4*)(S0 + (size_t)(ph + 2 * (16 * half + i)) * 128);
; #pragma unroll 1
;               for (int t = 0; t < 4; ++t) { const int row = TP + 4 * b + t; const float dtv = DT[(size_t)row * 32 + h]; const float dec = __expf(dtv * a);
;                   const u32x2 bw = *(const u32x2*)(XS + (size_t)row * 3072 + 2048 + g * 128 + n4), cw2 = *(const u32x2*)(XS + (size_t)row * 3072 + 2560 + g * 128 + n4);
;                   const f32x4 Bv = {bflo(bw.x), bfhi(bw.x), bflo(bw.y), bfhi(bw.y)}, Cv = {bflo(cw2.x), bfhi(cw2.x), bflo(cw2.y), bfhi(cw2.y)}; float ysel = 0.f;
; #pragma unroll
;                   for (int i = 0; i < 16; ++i) { const int p = ph + 2 * (16 * half + i); const float xv = bf2f(XS[(size_t)row * 3072 + h * 64 + p]);
;                       S[i] = S[i] * dec + Bv * (dtv * xv);
.LBB0_186:
	s_and_b32 s5, s16, 31
	s_lshl_b32 s17, s5, 7
	s_lshl_b32 s12, s5, 2
	s_and_b32 s5, s4, 31
	s_lshl_b32 s5, s5, 2
	v_mov_b32_e32 v0, s5
	global_load_dword v1, v0, s[76:77]
	global_load_dword v163, v0, s[78:79]
	s_lshl_b32 s6, s16, 5
	s_ashr_i32 s5, s4, 31
	s_and_b32 s13, s6, 0x300
	s_lshl_b64 s[6:7], s[4:5], 15
	v_lshl_add_u64 v[142:143], v[68:69], 0, s[6:7]
	v_mov_b32_e32 v87, v25
	v_mov_b32_e32 v89, v25
	v_lshl_add_u64 v[20:21], v[142:143], 0, v[88:89]
	v_mov_b32_e32 v91, v25
	s_waitcnt lgkmcnt(0)
	v_mov_b32_e32 v93, v25
	v_lshl_add_u64 v[30:31], v[142:143], 0, v[92:93]
	v_mov_b32_e32 v95, v25
	v_mov_b32_e32 v97, v25
	v_lshl_add_u64 v[38:39], v[142:143], 0, v[96:97]
	v_mov_b32_e32 v99, v25
	v_mov_b32_e32 v101, v25
	v_lshl_add_u64 v[46:47], v[142:143], 0, v[100:101]
	v_mov_b32_e32 v103, v25
	v_mov_b32_e32 v105, v25
	v_lshl_add_u64 v[54:55], v[142:143], 0, v[104:105]
	v_mov_b32_e32 v107, v25
	v_mov_b32_e32 v109, v25
	v_lshl_add_u64 v[62:63], v[142:143], 0, v[108:109]
	s_lshl_b64 s[8:9], s[4:5], 13
	s_ashr_i32 s5, s4, 3
	s_and_b32 s5, s5, -4
	s_add_i32 s6, s5, 0x4000
	s_ashr_i32 s7, s6, 31
	s_lshl_b64 s[10:11], s[6:7], 12
	s_mul_hi_i32 s5, s6, 0x1800
	s_mul_i32 s18, s6, 0x1800
	s_lshl_b64 s[6:7], s[6:7], 7
	s_or_b32 s14, s10, s17
	s_or_b32 s6, s6, s12
	s_add_u32 s6, s6, 0x26f70000
	s_mov_b32 s15, s11
	v_mov_b32_e32 v141, s5
	s_addc_u32 s7, s7, 0
	s_or_b32 s12, s18, s17
	v_lshl_add_u64 v[144:145], s[14:15], 0, v[72:73]
	s_mov_b32 s19, 4
	s_waitcnt vmcnt(1)
	v_mul_f32_e32 v1, 0x3fb8aa3b, v1
	v_exp_f32_e32 v162, v1
	v_lshl_add_u64 v[0:1], v[142:143], 0, v[24:25]
	global_load_dwordx4 v[16:19], v[0:1], off
	global_load_dwordx4 v[12:15], v[0:1], off offset:1024
	global_load_dwordx4 v[8:11], v[0:1], off offset:2048
	global_load_dwordx4 v[4:7], v[0:1], off offset:3072
	v_lshl_add_u64 v[0:1], v[142:143], 0, v[86:87]
	global_load_dwordx4 v[0:3], v[0:1], off
	v_or_b32_e32 v87, s18, v74
	global_load_dwordx4 v[26:29], v[20:21], off
	v_lshl_add_u64 v[20:21], v[142:143], 0, v[90:91]
	global_load_dwordx4 v[20:23], v[20:21], off
	v_or_b32_e32 v140, s13, v87
	global_load_dwordx4 v[34:37], v[30:31], off
	v_lshl_add_u64 v[30:31], v[142:143], 0, v[94:95]
	global_load_dwordx4 v[30:33], v[30:31], off
	s_mov_b32 s13, s5
	global_load_dwordx4 v[42:45], v[38:39], off
	v_lshl_add_u64 v[38:39], v[142:143], 0, v[98:99]
	global_load_dwordx4 v[38:41], v[38:39], off
	v_lshl_add_u64 v[146:147], s[12:13], 0, v[76:77]
	global_load_dwordx4 v[50:53], v[46:47], off
	v_lshl_add_u64 v[46:47], v[142:143], 0, v[102:103]
	global_load_dwordx4 v[46:49], v[46:47], off
	v_lshl_add_u64 v[148:149], s[12:13], 0, v[78:79]
	global_load_dwordx4 v[58:61], v[54:55], off
	v_lshl_add_u64 v[54:55], v[142:143], 0, v[106:107]
	global_load_dwordx4 v[54:57], v[54:55], off
	s_mov_b64 s[12:13], s[6:7]
	global_load_dwordx4 v[62:65], v[62:63], off
	v_mov_b64_e32 v[150:151], v[140:141]
	s_add_u32 s14, s26, s12
	s_addc_u32 s15, s27, s13
	global_load_dword v216, v25, s[14:15]
	v_lshl_add_u64 v[240:241], s[26:27], 0, v[150:151]
	v_add_co_u32_e64 v240, s[72:73], s90, v240
	s_nop 1
	v_addc_co_u32_e64 v241, s[72:73], 0, v241, s[72:73]
	global_load_dwordx2 v[218:219], v[240:241], off
	global_load_dwordx2 v[220:221], v[240:241], off offset:1024
	v_lshl_add_u64 v[240:241], s[26:27], 0, v[148:149]
	global_load_ushort v222, v[240:241], off offset:-32
	global_load_ushort v223, v[240:241], off offset:-28
	global_load_ushort v224, v[240:241], off offset:-24
	global_load_ushort v225, v[240:241], off offset:-20
	global_load_ushort v226, v[240:241], off offset:-16
	global_load_ushort v227, v[240:241], off offset:-12
	global_load_ushort v228, v[240:241], off offset:-8
	global_load_ushort v229, v[240:241], off offset:-4
	global_load_ushort v230, v[240:241], off
	global_load_ushort v231, v[240:241], off offset:4
	global_load_ushort v232, v[240:241], off offset:8
	global_load_ushort v233, v[240:241], off offset:12
	global_load_ushort v234, v[240:241], off offset:16
	global_load_ushort v235, v[240:241], off offset:20
	global_load_ushort v236, v[240:241], off offset:24
	global_load_ushort v237, v[240:241], off offset:28
	v_lshl_add_u64 v[240:241], s[26:27], 0, v[146:147]
	global_load_ushort v238, v[240:241], off
	s_waitcnt vmcnt(0)
	s_branch .Lssd_a_top
.LBB0_187:
	s_or_b64 exec, exec, s[14:15]
	s_add_i32 s19, s19, -1
	s_add_u32 s12, s12, 0x80
	s_addc_u32 s13, s13, 0
	v_lshl_add_u64 v[144:145], v[144:145], 0, s[70:71]
	v_lshl_add_u64 v[150:151], v[150:151], 0, s[30:31]
	v_lshl_add_u64 v[146:147], v[146:147], 0, s[30:31]
	s_cmp_eq_u32 s19, 0
	v_lshl_add_u64 v[148:149], v[148:149], 0, s[30:31]
	s_cbranch_scc1 .LBB0_190
.LBB0_188:
	s_waitcnt vmcnt(1)
; DI float bflo(unsigned w) { return __uint_as_float(w << 16); }
; DI float bfhi(unsigned w) { return __uint_as_float(w & 0xffff0000u); }
; DI float bf2f(bf16_t b) { return __uint_as_float(((unsigned)b) << 16); }
; DI void ssd_scan(const Params& P, LAS unsigned char* lds) {
;     ...
;               for (int t = 0; t < 4; ++t) { const int row = TP + 4 * b + t; const float dtv = DT[(size_t)row * 32 + h]; const float dec = __expf(dtv * a);
;                   const u32x2 bw = *(const u32x2*)(XS + (size_t)row * 3072 + 2048 + g * 128 + n4), cw2 = *(const u32x2*)(XS + (size_t)row * 3072 + 2560 + g * 128 + n4);
;                   const f32x4 Bv = {bflo(bw.x), bfhi(bw.x), bflo(bw.y), bfhi(bw.y)}, Cv = {bflo(cw2.x), bfhi(cw2.x), bflo(cw2.y), bfhi(cw2.y)}; float ysel = 0.f;
; #pragma unroll
;                   for (int i = 0; i < 16; ++i) { const int p = ph + 2 * (16 * half + i); const float xv = bf2f(XS[(size_t)row * 3072 + h * 64 + p]);
;                       S[i] = S[i] * dec + Bv * (dtv * xv);
.Lssd_a_top:
	s_waitcnt lgkmcnt(0)
	v_mov_b32_e32 v91, v216
	v_mul_f32_e32 v248, v216, v162
	v_mul_f32_e32 v248, 0xbfb8aa3b, v248
	v_exp_f32_e32 v152, v248
	v_lshlrev_b32_e32 v95, 16, v220
	v_and_b32_e32 v99, 0xffff0000, v220
	v_lshlrev_b32_e32 v93, 16, v221
	v_and_b32_e32 v97, 0xffff0000, v221
	v_lshlrev_b32_e32 v154, 16, v218
	v_and_b32_e32 v155, 0xffff0000, v218
	v_lshlrev_b32_e32 v156, 16, v219
	v_and_b32_e32 v157, 0xffff0000, v219
	v_mov_b32_e32 v87, v222
	v_mov_b32_e32 v101, v223
	v_mov_b32_e32 v105, v224
	v_mov_b32_e32 v109, v225
	v_mov_b32_e32 v113, v226
	v_mov_b32_e32 v117, v227
	v_mov_b32_e32 v121, v228
	v_mov_b32_e32 v125, v229
	v_mov_b32_e32 v129, v230
	v_mov_b32_e32 v133, v231
	v_mov_b32_e32 v137, v232
	v_mov_b32_e32 v166, v234
	v_mov_b32_e32 v242, v233
	v_mov_b32_e32 v243, v235
	v_mov_b32_e32 v244, v236
	v_mov_b32_e32 v245, v237
	v_mov_b32_e32 v239, v238
	s_cmp_eq_u32 s19, 1
	s_cbranch_scc1 .Lssd_a_nopf
	s_add_u32 s14, s26, s12
	s_addc_u32 s15, s27, s13
	s_add_u32 s14, s14, 0x80
	s_addc_u32 s15, s15, 0
	global_load_dword v216, v25, s[14:15]
	v_lshl_add_u64 v[240:241], v[150:151], 0, s[30:31]
	v_lshl_add_u64 v[240:241], s[26:27], 0, v[240:241]
	v_add_co_u32_e64 v240, s[72:73], s90, v240
	s_nop 1
	v_addc_co_u32_e64 v241, s[72:73], 0, v241, s[72:73]
	global_load_dwordx2 v[218:219], v[240:241], off
	global_load_dwordx2 v[220:221], v[240:241], off offset:1024
	v_lshl_add_u64 v[240:241], v[148:149], 0, s[30:31]
	v_lshl_add_u64 v[240:241], s[26:27], 0, v[240:241]
	global_load_ushort v222, v[240:241], off offset:-32
	global_load_ushort v223, v[240:241], off offset:-28
	global_load_ushort v224, v[240:241], off offset:-24
	global_load_ushort v225, v[240:241], off offset:-20
	global_load_ushort v226, v[240:241], off offset:-16
	global_load_ushort v227, v[240:241], off offset:-12
	global_load_ushort v228, v[240:241], off offset:-8
	global_load_ushort v229, v[240:241], off offset:-4
	global_load_ushort v230, v[240:241], off
	global_load_ushort v231, v[240:241], off offset:4
	global_load_ushort v232, v[240:241], off offset:8
	global_load_ushort v233, v[240:241], off offset:12
	global_load_ushort v234, v[240:241], off offset:16
	global_load_ushort v235, v[240:241], off offset:20
	global_load_ushort v236, v[240:241], off offset:24
	global_load_ushort v237, v[240:241], off offset:28
	v_lshl_add_u64 v[240:241], v[146:147], 0, s[30:31]
	v_lshl_add_u64 v[240:241], s[26:27], 0, v[240:241]
	global_load_ushort v238, v[240:241], off
.Lssd_a_nopf:
	v_lshlrev_b32_e32 v87, 16, v87
	v_mul_f32_e32 v164, v91, v87
	v_pk_mul_f32 v[168:169], v[164:165], v[154:155] op_sel_hi:[0,1]
	v_pk_mul_f32 v[164:165], v[164:165], v[156:157] op_sel_hi:[0,1]
	v_lshlrev_b32_e32 v101, 16, v101
	v_pk_fma_f32 v[18:19], v[18:19], v[152:153], v[164:165] op_sel_hi:[1,0,1]
	v_mul_f32_e32 v164, v91, v101
	v_pk_fma_f32 v[16:17], v[16:17], v[152:153], v[168:169] op_sel_hi:[1,0,1]
	v_pk_mul_f32 v[168:169], v[164:165], v[154:155] op_sel_hi:[0,1]
	v_pk_mul_f32 v[164:165], v[164:165], v[156:157] op_sel_hi:[0,1]
	v_lshlrev_b32_e32 v105, 16, v105
	v_pk_fma_f32 v[14:15], v[14:15], v[152:153], v[164:165] op_sel_hi:[1,0,1]
	v_mul_f32_e32 v164, v91, v105
	v_pk_fma_f32 v[12:13], v[12:13], v[152:153], v[168:169] op_sel_hi:[1,0,1]
	v_pk_mul_f32 v[168:169], v[164:165], v[154:155] op_sel_hi:[0,1]
	v_pk_mul_f32 v[164:165], v[164:165], v[156:157] op_sel_hi:[0,1]
	v_lshlrev_b32_e32 v109, 16, v109
	v_pk_fma_f32 v[10:11], v[10:11], v[152:153], v[164:165] op_sel_hi:[1,0,1]
	v_mul_f32_e32 v164, v91, v109
	v_pk_fma_f32 v[8:9], v[8:9], v[152:153], v[168:169] op_sel_hi:[1,0,1]
	v_pk_mul_f32 v[168:169], v[164:165], v[154:155] op_sel_hi:[0,1]
	v_pk_mul_f32 v[164:165], v[164:165], v[156:157] op_sel_hi:[0,1]
	v_lshlrev_b32_e32 v113, 16, v113
	v_pk_fma_f32 v[6:7], v[6:7], v[152:153], v[164:165] op_sel_hi:[1,0,1]
	v_mul_f32_e32 v164, v91, v113
	v_pk_fma_f32 v[4:5], v[4:5], v[152:153], v[168:169] op_sel_hi:[1,0,1]
	v_pk_mul_f32 v[168:169], v[164:165], v[154:155] op_sel_hi:[0,1]
	v_pk_mul_f32 v[164:165], v[164:165], v[156:157] op_sel_hi:[0,1]
	v_lshlrev_b32_e32 v117, 16, v117
	v_pk_fma_f32 v[2:3], v[2:3], v[152:153], v[164:165] op_sel_hi:[1,0,1]
	v_mul_f32_e32 v164, v91, v117
	v_pk_fma_f32 v[0:1], v[0:1], v[152:153], v[168:169] op_sel_hi:[1,0,1]
	v_pk_mul_f32 v[168:169], v[164:165], v[154:155] op_sel_hi:[0,1]
	v_pk_mul_f32 v[164:165], v[164:165], v[156:157] op_sel_hi:[0,1]
	v_lshlrev_b32_e32 v121, 16, v121
	v_pk_fma_f32 v[28:29], v[28:29], v[152:153], v[164:165] op_sel_hi:[1,0,1]
	v_mul_f32_e32 v164, v91, v121
	v_pk_fma_f32 v[26:27], v[26:27], v[152:153], v[168:169] op_sel_hi:[1,0,1]
	v_pk_mul_f32 v[168:169], v[164:165], v[154:155] op_sel_hi:[0,1]
	v_pk_mul_f32 v[164:165], v[164:165], v[156:157] op_sel_hi:[0,1]
	v_lshlrev_b32_e32 v125, 16, v125
	v_pk_fma_f32 v[22:23], v[22:23], v[152:153], v[164:165] op_sel_hi:[1,0,1]
	v_mul_f32_e32 v164, v91, v125
	v_pk_fma_f32 v[20:21], v[20:21], v[152:153], v[168:169] op_sel_hi:[1,0,1]
	v_pk_mul_f32 v[168:169], v[164:165], v[154:155] op_sel_hi:[0,1]
	v_pk_mul_f32 v[164:165], v[164:165], v[156:157] op_sel_hi:[0,1]
	v_lshlrev_b32_e32 v129, 16, v129
	v_pk_fma_f32 v[36:37], v[36:37], v[152:153], v[164:165] op_sel_hi:[1,0,1]
	v_mul_f32_e32 v164, v91, v129
	v_pk_fma_f32 v[34:35], v[34:35], v[152:153], v[168:169] op_sel_hi:[1,0,1]
	v_pk_mul_f32 v[168:169], v[164:165], v[154:155] op_sel_hi:[0,1]
	v_pk_mul_f32 v[164:165], v[164:165], v[156:157] op_sel_hi:[0,1]
	v_lshlrev_b32_e32 v133, 16, v133
	v_pk_fma_f32 v[32:33], v[32:33], v[152:153], v[164:165] op_sel_hi:[1,0,1]
	v_mul_f32_e32 v164, v91, v133
	v_pk_fma_f32 v[30:31], v[30:31], v[152:153], v[168:169] op_sel_hi:[1,0,1]
; DI float bf2f(bf16_t b) { return __uint_as_float(((unsigned)b) << 16); }
; DI void ssd_scan(const Params& P, LAS unsigned char* lds) {
;     ...
;                   for (int i = 0; i < 16; ++i) { const int p = ph + 2 * (16 * half + i); const float xv = bf2f(XS[(size_t)row * 3072 + h * 64 + p]);
;                       S[i] = S[i] * dec + Bv * (dtv * xv);
;                       float yp = (S[i][0] * Cv[0] + S[i][1] * Cv[1]) + (S[i][2] * Cv[2] + S[i][3] * Cv[3]);
;                       yp += __shfl_xor(yp, 1); yp += __shfl_xor(yp, 2); yp += __shfl_xor(yp, 4); yp += __shfl_xor(yp, 8); yp += __shfl_xor(yp, 16);
;                       ysel = ((lane & 31) == i) ? yp : ysel; }
	v_pk_mul_f32 v[168:169], v[164:165], v[154:155] op_sel_hi:[0,1]
	v_pk_mul_f32 v[164:165], v[164:165], v[156:157] op_sel_hi:[0,1]
	v_lshlrev_b32_e32 v137, 16, v137
	v_pk_fma_f32 v[44:45], v[44:45], v[152:153], v[164:165] op_sel_hi:[1,0,1]
	v_mul_f32_e32 v164, v91, v137
	v_pk_fma_f32 v[42:43], v[42:43], v[152:153], v[168:169] op_sel_hi:[1,0,1]
	v_pk_mul_f32 v[168:169], v[164:165], v[154:155] op_sel_hi:[0,1]
	v_pk_mul_f32 v[164:165], v[164:165], v[156:157] op_sel_hi:[0,1]
	v_pk_fma_f32 v[40:41], v[40:41], v[152:153], v[164:165] op_sel_hi:[1,0,1]
	v_mov_b32_e32 v164, v242
	v_lshlrev_b32_e32 v166, 16, v166
	v_pk_fma_f32 v[38:39], v[38:39], v[152:153], v[168:169] op_sel_hi:[1,0,1]
	v_mul_f32_e32 v166, v91, v166
	v_pk_mul_f32 v[170:171], v[166:167], v[156:157] op_sel_hi:[0,1]
	v_pk_fma_f32 v[48:49], v[48:49], v[152:153], v[170:171] op_sel_hi:[1,0,1]
	v_mul_f32_e32 v87, v17, v99
	v_mul_f32_e32 v101, v13, v99
	v_mul_f32_e32 v105, v9, v99
	v_mul_f32_e32 v109, v5, v99
	v_mul_f32_e32 v113, v1, v99
	v_mul_f32_e32 v117, v27, v99
	v_mul_f32_e32 v121, v21, v99
	v_mul_f32_e32 v125, v35, v99
	v_mul_f32_e32 v129, v31, v99
	v_mul_f32_e32 v133, v43, v99
	v_mul_f32_e32 v137, v39, v99
	v_fmac_f32_e32 v87, v16, v95
	v_mul_f32_e32 v89, v19, v97
	v_fmac_f32_e32 v101, v12, v95
	v_mul_f32_e32 v103, v15, v97
	v_fmac_f32_e32 v105, v8, v95
	v_mul_f32_e32 v107, v11, v97
	v_fmac_f32_e32 v109, v4, v95
	v_mul_f32_e32 v111, v7, v97
	v_fmac_f32_e32 v113, v0, v95
	v_mul_f32_e32 v115, v3, v97
	v_fmac_f32_e32 v117, v26, v95
	v_mul_f32_e32 v119, v29, v97
	v_fmac_f32_e32 v121, v20, v95
	v_mul_f32_e32 v123, v23, v97
	v_fmac_f32_e32 v125, v34, v95
	v_mul_f32_e32 v127, v37, v97
	v_fmac_f32_e32 v129, v30, v95
	v_mul_f32_e32 v131, v33, v97
	v_fmac_f32_e32 v133, v42, v95
	v_mul_f32_e32 v135, v45, v97
	v_fmac_f32_e32 v137, v38, v95
	v_mul_f32_e32 v139, v41, v97
	v_fmac_f32_e32 v89, v18, v93
	v_fmac_f32_e32 v103, v14, v93
	v_fmac_f32_e32 v107, v10, v93
	v_fmac_f32_e32 v111, v6, v93
	v_fmac_f32_e32 v115, v2, v93
	v_fmac_f32_e32 v119, v28, v93
	v_fmac_f32_e32 v123, v22, v93
	v_fmac_f32_e32 v127, v36, v93
	v_fmac_f32_e32 v131, v32, v93
	v_fmac_f32_e32 v135, v44, v93
	v_fmac_f32_e32 v139, v40, v93
	v_add_f32_e32 v87, v87, v89
	v_add_f32_e32 v101, v101, v103
	v_add_f32_e32 v105, v105, v107
	v_add_f32_e32 v109, v109, v111
	v_add_f32_e32 v113, v113, v115
	v_add_f32_e32 v117, v117, v119
	v_add_f32_e32 v121, v121, v123
	v_add_f32_e32 v125, v125, v127
	v_add_f32_e32 v129, v129, v131
	v_add_f32_e32 v133, v133, v135
	v_add_f32_e32 v137, v137, v139
	ds_bpermute_b32 v89, v67, v87
	ds_bpermute_b32 v103, v67, v101
	ds_bpermute_b32 v107, v67, v105
	ds_bpermute_b32 v111, v67, v109
	ds_bpermute_b32 v115, v67, v113
	ds_bpermute_b32 v119, v67, v117
	ds_bpermute_b32 v123, v67, v121
	ds_bpermute_b32 v127, v67, v125
	ds_bpermute_b32 v131, v67, v129
	ds_bpermute_b32 v135, v67, v133
	ds_bpermute_b32 v139, v67, v137
	s_waitcnt lgkmcnt(10)
	v_add_f32_e32 v87, v87, v89
	s_waitcnt lgkmcnt(9)
	v_add_f32_e32 v101, v101, v103
	s_waitcnt lgkmcnt(8)
	v_add_f32_e32 v105, v105, v107
	s_waitcnt lgkmcnt(7)
	v_add_f32_e32 v109, v109, v111
	s_waitcnt lgkmcnt(6)
	v_add_f32_e32 v113, v113, v115
	s_waitcnt lgkmcnt(5)
	v_add_f32_e32 v117, v117, v119
	s_waitcnt lgkmcnt(4)
	v_add_f32_e32 v121, v121, v123
	s_waitcnt lgkmcnt(3)
	v_add_f32_e32 v125, v125, v127
	v_lshlrev_b32_e32 v164, 16, v164
	v_mul_f32_e32 v164, v91, v164
	v_pk_mul_f32 v[168:169], v[164:165], v[154:155] op_sel_hi:[0,1]
	v_pk_fma_f32 v[50:51], v[50:51], v[152:153], v[168:169] op_sel_hi:[1,0,1]
	v_pk_mul_f32 v[168:169], v[166:167], v[154:155] op_sel_hi:[0,1]
	v_pk_fma_f32 v[46:47], v[46:47], v[152:153], v[168:169] op_sel_hi:[1,0,1]
	v_mov_b32_e32 v169, v243
	v_pk_mul_f32 v[164:165], v[164:165], v[156:157] op_sel_hi:[0,1]
	v_pk_fma_f32 v[52:53], v[52:53], v[152:153], v[164:165] op_sel_hi:[1,0,1]
	v_mul_f32_e32 v164, v51, v99
	v_mul_f32_e32 v166, v47, v99
	v_fmac_f32_e32 v164, v50, v95
	v_mul_f32_e32 v165, v53, v97
	v_fmac_f32_e32 v166, v46, v95
	v_mul_f32_e32 v168, v49, v97
	v_fmac_f32_e32 v165, v52, v93
	v_fmac_f32_e32 v168, v48, v93
	v_add_f32_e32 v164, v164, v165
	v_add_f32_e32 v166, v166, v168
	ds_bpermute_b32 v165, v67, v164
	ds_bpermute_b32 v168, v67, v166
	s_waitcnt lgkmcnt(4)
	v_add_f32_e32 v129, v129, v131
	s_waitcnt lgkmcnt(3)
	v_add_f32_e32 v133, v133, v135
	s_waitcnt lgkmcnt(2)
	v_add_f32_e32 v137, v137, v139
	s_waitcnt lgkmcnt(1)
	v_add_f32_e32 v164, v164, v165
	s_waitcnt lgkmcnt(0)
	v_add_f32_e32 v166, v166, v168
	ds_bpermute_b32 v89, v75, v87
	ds_bpermute_b32 v103, v75, v101
	ds_bpermute_b32 v107, v75, v105
	ds_bpermute_b32 v111, v75, v109
	ds_bpermute_b32 v115, v75, v113
	ds_bpermute_b32 v119, v75, v117
	ds_bpermute_b32 v123, v75, v121
	ds_bpermute_b32 v127, v75, v125
	ds_bpermute_b32 v131, v75, v129
	ds_bpermute_b32 v135, v75, v133
	ds_bpermute_b32 v139, v75, v137
	ds_bpermute_b32 v165, v75, v164
	ds_bpermute_b32 v168, v75, v166
	s_waitcnt lgkmcnt(12)
	v_add_f32_e32 v87, v87, v89
	s_waitcnt lgkmcnt(11)
	v_add_f32_e32 v101, v101, v103
	s_waitcnt lgkmcnt(10)
	v_add_f32_e32 v105, v105, v107
	s_waitcnt lgkmcnt(9)
	v_add_f32_e32 v109, v109, v111
	s_waitcnt lgkmcnt(8)
	v_add_f32_e32 v113, v113, v115
	s_waitcnt lgkmcnt(7)
	v_add_f32_e32 v117, v117, v119
	s_waitcnt lgkmcnt(6)
	v_add_f32_e32 v121, v121, v123
	s_waitcnt lgkmcnt(5)
	v_add_f32_e32 v125, v125, v127
	s_waitcnt lgkmcnt(4)
	v_add_f32_e32 v129, v129, v131
	s_waitcnt lgkmcnt(3)
	v_add_f32_e32 v133, v133, v135
	s_waitcnt lgkmcnt(2)
	v_add_f32_e32 v137, v137, v139
	s_waitcnt lgkmcnt(1)
	v_add_f32_e32 v164, v164, v165
	s_waitcnt lgkmcnt(0)
; DI float bf2f(bf16_t b) { return __uint_as_float(((unsigned)b) << 16); }
; DI bf16_t f2bf(float f) { return (bf16_t)(pk2(f, 0.f) & 0xffffu); }
; DI void ssd_scan(const Params& P, LAS unsigned char* lds) {
;     ...
;                       float yp = (S[i][0] * Cv[0] + S[i][1] * Cv[1]) + (S[i][2] * Cv[2] + S[i][3] * Cv[3]);
;                       yp += __shfl_xor(yp, 1); yp += __shfl_xor(yp, 2); yp += __shfl_xor(yp, 4); yp += __shfl_xor(yp, 8); yp += __shfl_xor(yp, 16);
;                       ysel = ((lane & 31) == i) ? yp : ysel; }
;                   if ((lane & 31) < 16) { const int p = ph + 2 * (16 * half + (lane & 31)); const float xv = bf2f(XS[(size_t)row * 3072 + h * 64 + p]);
;                       YB[(size_t)row * 2048 + h * 64 + p] = f2bf(ysel + dsk * xv); } }
	v_add_f32_e32 v166, v166, v168
	ds_bpermute_b32 v89, v153, v87
	ds_bpermute_b32 v103, v153, v101
	ds_bpermute_b32 v107, v153, v105
	ds_bpermute_b32 v111, v153, v109
	ds_bpermute_b32 v115, v153, v113
	ds_bpermute_b32 v119, v153, v117
	ds_bpermute_b32 v123, v153, v121
	ds_bpermute_b32 v127, v153, v125
	ds_bpermute_b32 v131, v153, v129
	ds_bpermute_b32 v135, v153, v133
	ds_bpermute_b32 v139, v153, v137
	ds_bpermute_b32 v165, v153, v164
	ds_bpermute_b32 v168, v153, v166
	s_waitcnt lgkmcnt(12)
	v_add_f32_e32 v87, v87, v89
	s_waitcnt lgkmcnt(11)
	v_add_f32_e32 v101, v101, v103
	s_waitcnt lgkmcnt(10)
	v_add_f32_e32 v105, v105, v107
	s_waitcnt lgkmcnt(9)
	v_add_f32_e32 v109, v109, v111
	s_waitcnt lgkmcnt(8)
	v_add_f32_e32 v113, v113, v115
	s_waitcnt lgkmcnt(7)
	v_add_f32_e32 v117, v117, v119
	s_waitcnt lgkmcnt(6)
	v_add_f32_e32 v121, v121, v123
	s_waitcnt lgkmcnt(5)
	v_add_f32_e32 v125, v125, v127
	s_waitcnt lgkmcnt(4)
	v_add_f32_e32 v129, v129, v131
	s_waitcnt lgkmcnt(3)
	v_add_f32_e32 v133, v133, v135
	s_waitcnt lgkmcnt(2)
	v_add_f32_e32 v137, v137, v139
	s_waitcnt lgkmcnt(1)
	v_add_f32_e32 v164, v164, v165
	s_waitcnt lgkmcnt(0)
	v_add_f32_e32 v166, v166, v168
	ds_bpermute_b32 v89, v160, v87
	ds_bpermute_b32 v103, v160, v101
	ds_bpermute_b32 v107, v160, v105
	ds_bpermute_b32 v111, v160, v109
	ds_bpermute_b32 v115, v160, v113
	ds_bpermute_b32 v119, v160, v117
	ds_bpermute_b32 v123, v160, v121
	ds_bpermute_b32 v127, v160, v125
	v_lshlrev_b32_e32 v169, 16, v169
	v_mul_f32_e32 v170, v91, v169
	v_pk_mul_f32 v[172:173], v[170:171], v[154:155] op_sel_hi:[0,1]
	v_pk_mul_f32 v[170:171], v[170:171], v[156:157] op_sel_hi:[0,1]
	v_pk_fma_f32 v[60:61], v[60:61], v[152:153], v[170:171] op_sel_hi:[1,0,1]
	v_mov_b32_e32 v171, v244
	v_pk_fma_f32 v[58:59], v[58:59], v[152:153], v[172:173] op_sel_hi:[1,0,1]
	v_mov_b32_e32 v158, v245
	v_mul_f32_e32 v169, v59, v99
	v_fmac_f32_e32 v169, v58, v95
	v_mul_f32_e32 v170, v61, v97
	v_fmac_f32_e32 v170, v60, v93
	v_add_f32_e32 v169, v169, v170
	ds_bpermute_b32 v170, v67, v169
	ds_bpermute_b32 v131, v160, v129
	ds_bpermute_b32 v135, v160, v133
	ds_bpermute_b32 v139, v160, v137
	ds_bpermute_b32 v165, v160, v164
	s_waitcnt lgkmcnt(4)
	v_add_f32_e32 v169, v169, v170
	ds_bpermute_b32 v170, v75, v169
	ds_bpermute_b32 v168, v160, v166
	v_add_f32_e32 v87, v87, v89
	v_add_f32_e32 v101, v101, v103
	v_add_f32_e32 v105, v105, v107
	s_waitcnt lgkmcnt(1)
	v_add_f32_e32 v169, v169, v170
	ds_bpermute_b32 v170, v153, v169
	v_add_f32_e32 v109, v109, v111
	v_add_f32_e32 v113, v113, v115
	v_add_f32_e32 v117, v117, v119
	v_add_f32_e32 v121, v121, v123
	s_waitcnt lgkmcnt(0)
	v_add_f32_e32 v169, v169, v170
	ds_bpermute_b32 v170, v160, v169
	v_add_f32_e32 v125, v125, v127
	v_add_f32_e32 v129, v129, v131
	v_add_f32_e32 v133, v133, v135
	v_add_f32_e32 v137, v137, v139
	v_add_f32_e32 v164, v164, v165
	v_add_f32_e32 v166, v166, v168
	s_waitcnt lgkmcnt(0)
	v_add_f32_e32 v169, v169, v170
	ds_bpermute_b32 v89, v161, v87
	ds_bpermute_b32 v103, v161, v101
	ds_bpermute_b32 v107, v161, v105
	ds_bpermute_b32 v111, v161, v109
	ds_bpermute_b32 v115, v161, v113
	ds_bpermute_b32 v119, v161, v117
	ds_bpermute_b32 v123, v161, v121
	ds_bpermute_b32 v127, v161, v125
	ds_bpermute_b32 v131, v161, v129
	ds_bpermute_b32 v135, v161, v133
	ds_bpermute_b32 v139, v161, v137
	ds_bpermute_b32 v165, v161, v164
	ds_bpermute_b32 v168, v161, v166
	ds_bpermute_b32 v170, v161, v169
	v_lshlrev_b32_e32 v171, 16, v171
	v_mul_f32_e32 v172, v91, v171
	v_lshlrev_b32_e32 v158, 16, v158
	v_mul_f32_e32 v158, v91, v158
	v_pk_mul_f32 v[174:175], v[172:173], v[154:155] op_sel_hi:[0,1]
	v_pk_mul_f32 v[154:155], v[158:159], v[154:155] op_sel_hi:[0,1]
	v_pk_mul_f32 v[172:173], v[172:173], v[156:157] op_sel_hi:[0,1]
	v_pk_fma_f32 v[54:55], v[54:55], v[152:153], v[174:175] op_sel_hi:[1,0,1]
	v_pk_mul_f32 v[156:157], v[158:159], v[156:157] op_sel_hi:[0,1]
	v_pk_fma_f32 v[62:63], v[62:63], v[152:153], v[154:155] op_sel_hi:[1,0,1]
	v_pk_fma_f32 v[56:57], v[56:57], v[152:153], v[172:173] op_sel_hi:[1,0,1]
	v_mul_f32_e32 v171, v55, v99
	v_pk_fma_f32 v[64:65], v[64:65], v[152:153], v[156:157] op_sel_hi:[1,0,1]
	v_mul_f32_e32 v91, v63, v99
	v_fmac_f32_e32 v171, v54, v95
	v_mul_f32_e32 v172, v57, v97
	v_fmac_f32_e32 v91, v62, v95
	v_mul_f32_e32 v95, v65, v97
	v_fmac_f32_e32 v172, v56, v93
	v_fmac_f32_e32 v95, v64, v93
	v_add_f32_e32 v171, v171, v172
	v_add_f32_e32 v91, v91, v95
	ds_bpermute_b32 v172, v67, v171
	ds_bpermute_b32 v93, v67, v91
	s_waitcnt lgkmcnt(1)
	v_add_f32_e32 v171, v171, v172
	s_waitcnt lgkmcnt(0)
	v_add_f32_e32 v91, v91, v93
	ds_bpermute_b32 v172, v75, v171
	ds_bpermute_b32 v93, v75, v91
	s_waitcnt lgkmcnt(1)
	v_add_f32_e32 v171, v171, v172
	s_waitcnt lgkmcnt(0)
	v_add_f32_e32 v91, v91, v93
	ds_bpermute_b32 v172, v153, v171
	ds_bpermute_b32 v93, v153, v91
	s_waitcnt lgkmcnt(1)
	v_add_f32_e32 v171, v171, v172
	s_waitcnt lgkmcnt(0)
	v_add_f32_e32 v91, v91, v93
	ds_bpermute_b32 v172, v160, v171
	ds_bpermute_b32 v93, v160, v91
	s_waitcnt lgkmcnt(1)
	v_add_f32_e32 v171, v171, v172
	s_waitcnt lgkmcnt(0)
	v_add_f32_e32 v91, v91, v93
	ds_bpermute_b32 v172, v161, v171
	ds_bpermute_b32 v93, v161, v91
	s_and_saveexec_b64 s[14:15], vcc
	s_cbranch_execz .LBB0_187
	v_lshl_add_u64 v[154:155], s[26:27], 0, v[146:147]
	v_add_f32_e32 v87, v87, v89
	v_mov_b32_e32 v89, v239
	v_add_f32_e32 v101, v101, v103
	v_cndmask_b32_e64 v87, 0, v87, s[38:39]
	v_add_f32_e32 v105, v105, v107
	v_cndmask_b32_e64 v87, v87, v101, s[40:41]
	v_add_f32_e32 v109, v109, v111
	v_cndmask_b32_e64 v87, v87, v105, s[42:43]
	v_add_f32_e32 v113, v113, v115
	v_cndmask_b32_e64 v87, v87, v109, s[44:45]
	v_add_f32_e32 v117, v117, v119
	v_cndmask_b32_e64 v87, v87, v113, s[46:47]
	v_add_f32_e32 v121, v121, v123
	v_cndmask_b32_e64 v87, v87, v117, s[48:49]
	v_add_f32_e32 v125, v125, v127
	v_cndmask_b32_e64 v87, v87, v121, s[50:51]
	v_add_f32_e32 v129, v129, v131
	v_cndmask_b32_e64 v87, v87, v125, s[52:53]
	v_add_f32_e32 v133, v133, v135
	v_cndmask_b32_e64 v87, v87, v129, s[54:55]
	v_add_f32_e32 v137, v137, v139
	v_cndmask_b32_e64 v87, v87, v133, s[56:57]
	v_add_f32_e32 v99, v164, v165
	v_cndmask_b32_e64 v87, v87, v137, s[58:59]
	v_add_f32_e32 v97, v166, v168
	v_cndmask_b32_e64 v87, v87, v99, s[60:61]
	v_add_f32_e32 v95, v169, v170
	v_cndmask_b32_e64 v87, v87, v97, s[62:63]
	s_waitcnt lgkmcnt(0)
	v_add_f32_e32 v91, v91, v93
	v_add_f32_e32 v93, v171, v172
	v_cndmask_b32_e64 v87, v87, v95, s[64:65]
	v_cndmask_b32_e64 v87, v87, v93, s[66:67]
	v_cndmask_b32_e64 v87, v87, v91, s[68:69]
	v_lshl_add_u64 v[154:155], s[26:27], 0, v[144:145]
	v_lshlrev_b32_e32 v89, 16, v89
	v_fmac_f32_e32 v87, v163, v89
	v_cvt_pk_bf16_f32 v87, v87, s0
	global_store_short v[154:155], v87, off
	s_branch .LBB0_187
; DI void ssd_scan(const Params& P, LAS unsigned char* lds) {
;     ...
;           for (int half = 0; half < 2; ++half) { f32x4 S[16];
; #pragma unroll
;               for (int i = 0; i < 16; ++i) S[i] = *(const f32x4*)(S0 + (size_t)(ph + 2 * (16 * half + i)) * 128);
; #pragma unroll 1
;               for (int t = 0; t < 4; ++t) { const int row = TP + 4 * b + t; const float dtv = DT[(size_t)row * 32 + h]; const float dec = __expf(dtv * a);
;                   const u32x2 bw = *(const u32x2*)(XS + (size_t)row * 3072 + 2048 + g * 128 + n4), cw2 = *(const u32x2*)(XS + (size_t)row * 3072 + 2560 + g * 128 + n4);
;     ...
; #pragma unroll
;               for (int i = 0; i < 16; ++i) *(f32x4*)(SO + (size_t)(ph + 2 * (16 * half + i)) * 128) = S[i]; } } }
.LBB0_190:
	v_lshl_add_u64 v[144:145], s[8:9], 2, v[70:71]
	v_lshl_add_u64 v[146:147], v[144:145], 0, v[24:25]
	v_mov_b32_e32 v87, v25
	global_store_dwordx4 v[146:147], v[16:19], off
	global_store_dwordx4 v[146:147], v[12:15], off offset:1024
	global_store_dwordx4 v[146:147], v[8:11], off offset:2048
	global_store_dwordx4 v[146:147], v[4:7], off offset:3072
	v_mov_b32_e32 v89, v25
	v_mov_b32_e32 v91, v25
	v_lshl_add_u64 v[4:5], v[144:145], 0, v[86:87]
	global_store_dwordx4 v[4:5], v[0:3], off
	s_waitcnt lgkmcnt(0)
	v_mov_b32_e32 v93, v25
	v_mov_b32_e32 v95, v25
	v_lshl_add_u64 v[0:1], v[144:145], 0, v[88:89]
	global_store_dwordx4 v[0:1], v[26:29], off
	v_lshl_add_u64 v[0:1], v[144:145], 0, v[90:91]
	global_store_dwordx4 v[0:1], v[20:23], off
	v_lshl_add_u64 v[0:1], v[144:145], 0, v[92:93]
	global_store_dwordx4 v[0:1], v[34:37], off
	v_lshl_add_u64 v[0:1], v[144:145], 0, v[94:95]
	v_mov_b32_e32 v97, v25
	global_store_dwordx4 v[0:1], v[30:33], off
	v_lshl_add_u64 v[0:1], v[144:145], 0, v[96:97]
	v_mov_b32_e32 v99, v25
	global_store_dwordx4 v[0:1], v[42:45], off
	v_lshl_add_u64 v[0:1], v[144:145], 0, v[98:99]
	v_mov_b32_e32 v101, v25
	global_store_dwordx4 v[0:1], v[38:41], off
	v_lshl_add_u64 v[0:1], v[144:145], 0, v[100:101]
	v_mov_b32_e32 v103, v25
	global_store_dwordx4 v[0:1], v[50:53], off
	v_lshl_add_u64 v[0:1], v[144:145], 0, v[102:103]
	v_mov_b32_e32 v105, v25
	global_store_dwordx4 v[0:1], v[46:49], off
	v_lshl_add_u64 v[0:1], v[144:145], 0, v[104:105]
	v_mov_b32_e32 v107, v25
	global_store_dwordx4 v[0:1], v[58:61], off
	v_lshl_add_u64 v[0:1], v[144:145], 0, v[106:107]
	v_mov_b32_e32 v109, v25
	global_store_dwordx4 v[0:1], v[54:57], off
	v_lshl_add_u64 v[0:1], v[144:145], 0, v[108:109]
	v_lshlrev_b32_e32 v146, 2, v66
	v_mov_b32_e32 v147, v25
	v_mov_b32_e32 v111, v25
	v_mov_b32_e32 v113, v25
	v_mov_b32_e32 v115, v25
	v_mov_b32_e32 v117, v25
	v_mov_b32_e32 v119, v25
	v_mov_b32_e32 v121, v25
	v_mov_b32_e32 v123, v25
	global_store_dwordx4 v[0:1], v[62:65], off
	v_lshl_add_u64 v[0:1], v[142:143], 0, v[146:147]
	v_lshl_add_u64 v[2:3], v[142:143], 0, v[110:111]
	v_lshl_add_u64 v[4:5], v[142:143], 0, v[112:113]
	v_lshl_add_u64 v[6:7], v[142:143], 0, v[114:115]
	v_lshl_add_u64 v[8:9], v[142:143], 0, v[116:117]
	v_lshl_add_u64 v[10:11], v[142:143], 0, v[118:119]
	v_lshl_add_u64 v[12:13], v[142:143], 0, v[120:121]
	v_lshl_add_u64 v[14:15], v[142:143], 0, v[122:123]
	v_mov_b32_e32 v125, v25
	v_mov_b32_e32 v127, v25
	global_load_dwordx4 v[20:23], v[0:1], off
	s_nop 0
	global_load_dwordx4 v[0:3], v[2:3], off
	s_nop 0
	global_load_dwordx4 v[30:33], v[4:5], off
	s_nop 0
	global_load_dwordx4 v[4:7], v[6:7], off
	s_nop 0
	global_load_dwordx4 v[38:41], v[8:9], off
	s_nop 0
	global_load_dwordx4 v[8:11], v[10:11], off
	s_nop 0
	global_load_dwordx4 v[46:49], v[12:13], off
	global_load_dwordx4 v[16:19], v[14:15], off
	v_lshl_add_u64 v[12:13], v[142:143], 0, v[124:125]
	v_lshl_add_u64 v[14:15], v[142:143], 0, v[126:127]
	v_mov_b32_e32 v129, v25
	v_mov_b32_e32 v131, v25
	global_load_dwordx4 v[50:53], v[12:13], off
	global_load_dwordx4 v[26:29], v[14:15], off
	v_lshl_add_u64 v[12:13], v[142:143], 0, v[128:129]
	v_lshl_add_u64 v[14:15], v[142:143], 0, v[130:131]
	v_mov_b32_e32 v133, v25
	v_mov_b32_e32 v135, v25
	global_load_dwordx4 v[54:57], v[12:13], off
	global_load_dwordx4 v[34:37], v[14:15], off
	v_lshl_add_u64 v[12:13], v[142:143], 0, v[132:133]
	v_lshl_add_u64 v[14:15], v[142:143], 0, v[134:135]
	v_mov_b32_e32 v137, v25
	v_mov_b32_e32 v139, v25
	global_load_dwordx4 v[58:61], v[12:13], off
	global_load_dwordx4 v[42:45], v[14:15], off
	v_lshl_add_u64 v[12:13], v[142:143], 0, v[136:137]
	v_lshl_add_u64 v[14:15], v[142:143], 0, v[138:139]
	global_load_dwordx4 v[62:65], v[12:13], off
	s_nop 0
	global_load_dwordx4 v[12:15], v[14:15], off
	s_add_u32 s8, s17, s10
	s_addc_u32 s9, 0, s11
	v_lshl_add_u64 v[142:143], s[8:9], 0, v[80:81]
	s_add_u32 s8, s17, s18
	s_addc_u32 s9, 0, s5
	v_lshl_add_u64 v[148:149], s[8:9], 0, v[82:83]
	v_lshl_add_u64 v[150:151], s[8:9], 0, v[84:85]
	s_mov_b32 s5, 4
	s_add_u32 s8, s26, s6
	s_addc_u32 s9, s27, s7
	global_load_dword v216, v25, s[8:9]
	v_lshl_add_u64 v[240:241], s[26:27], 0, v[140:141]
	v_add_co_u32_e64 v240, s[72:73], s90, v240
	s_nop 1
	v_addc_co_u32_e64 v241, s[72:73], 0, v241, s[72:73]
	global_load_dwordx2 v[218:219], v[240:241], off
	global_load_dwordx2 v[220:221], v[240:241], off offset:1024
	v_lshl_add_u64 v[240:241], s[26:27], 0, v[150:151]
	global_load_ushort v222, v[240:241], off offset:-32
	global_load_ushort v223, v[240:241], off offset:-28
	global_load_ushort v224, v[240:241], off offset:-24
	global_load_ushort v225, v[240:241], off offset:-20
	global_load_ushort v226, v[240:241], off offset:-16
	global_load_ushort v227, v[240:241], off offset:-12
	global_load_ushort v228, v[240:241], off offset:-8
	global_load_ushort v229, v[240:241], off offset:-4
	global_load_ushort v230, v[240:241], off
	global_load_ushort v231, v[240:241], off offset:4
	global_load_ushort v232, v[240:241], off offset:8
	global_load_ushort v233, v[240:241], off offset:12
	global_load_ushort v234, v[240:241], off offset:16
	global_load_ushort v235, v[240:241], off offset:20
	global_load_ushort v236, v[240:241], off offset:24
	global_load_ushort v237, v[240:241], off offset:28
	v_lshl_add_u64 v[240:241], s[26:27], 0, v[148:149]
	global_load_ushort v238, v[240:241], off
	s_waitcnt vmcnt(0)
	s_branch .Lssd_b_top
.LBB0_191:
	s_or_b64 exec, exec, s[8:9]
	s_add_i32 s5, s5, -1
	s_add_u32 s6, s6, 0x80
	s_addc_u32 s7, s7, 0
	v_lshl_add_u64 v[142:143], v[142:143], 0, s[70:71]
	v_lshl_add_u64 v[140:141], v[140:141], 0, s[30:31]
	v_lshl_add_u64 v[148:149], v[148:149], 0, s[30:31]
	s_cmp_lg_u32 s5, 0
	v_lshl_add_u64 v[150:151], v[150:151], 0, s[30:31]
	s_cbranch_scc0 .LBB0_185
; DI float bflo(unsigned w) { return __uint_as_float(w << 16); }
; DI float bfhi(unsigned w) { return __uint_as_float(w & 0xffff0000u); }
; DI float bf2f(bf16_t b) { return __uint_as_float(((unsigned)b) << 16); }
; DI void ssd_scan(const Params& P, LAS unsigned char* lds) {
;     ...
;               for (int t = 0; t < 4; ++t) { const int row = TP + 4 * b + t; const float dtv = DT[(size_t)row * 32 + h]; const float dec = __expf(dtv * a);
;                   const u32x2 bw = *(const u32x2*)(XS + (size_t)row * 3072 + 2048 + g * 128 + n4), cw2 = *(const u32x2*)(XS + (size_t)row * 3072 + 2560 + g * 128 + n4);
;                   const f32x4 Bv = {bflo(bw.x), bfhi(bw.x), bflo(bw.y), bfhi(bw.y)}, Cv = {bflo(cw2.x), bfhi(cw2.x), bflo(cw2.y), bfhi(cw2.y)}; float ysel = 0.f;
; #pragma unroll
;                   for (int i = 0; i < 16; ++i) { const int p = ph + 2 * (16 * half + i); const float xv = bf2f(XS[(size_t)row * 3072 + h * 64 + p]);
;                       S[i] = S[i] * dec + Bv * (dtv * xv);
.LBB0_192:
	s_waitcnt vmcnt(1)
.Lssd_b_top:
	s_waitcnt lgkmcnt(0)
	v_mov_b32_e32 v91, v216
	v_mul_f32_e32 v248, v216, v162
	v_mul_f32_e32 v248, 0xbfb8aa3b, v248
	v_exp_f32_e32 v152, v248
	v_lshlrev_b32_e32 v95, 16, v220
	v_and_b32_e32 v99, 0xffff0000, v220
	v_lshlrev_b32_e32 v93, 16, v221
	v_and_b32_e32 v97, 0xffff0000, v221
	v_lshlrev_b32_e32 v154, 16, v218
	v_and_b32_e32 v155, 0xffff0000, v218
	v_lshlrev_b32_e32 v156, 16, v219
	v_and_b32_e32 v157, 0xffff0000, v219
	v_mov_b32_e32 v87, v222
	v_mov_b32_e32 v101, v223
	v_mov_b32_e32 v105, v224
	v_mov_b32_e32 v109, v225
	v_mov_b32_e32 v113, v226
	v_mov_b32_e32 v117, v227
	v_mov_b32_e32 v121, v228
	v_mov_b32_e32 v125, v229
	v_mov_b32_e32 v129, v230
	v_mov_b32_e32 v133, v231
	v_mov_b32_e32 v137, v232
	v_mov_b32_e32 v147, v233
	v_mov_b32_e32 v242, v234
	v_mov_b32_e32 v243, v235
	v_mov_b32_e32 v244, v236
	v_mov_b32_e32 v245, v237
	v_mov_b32_e32 v239, v238
	s_cmp_eq_u32 s5, 1
	s_cbranch_scc1 .Lssd_b_nopf
	s_add_u32 s8, s26, s6
	s_addc_u32 s9, s27, s7
	s_add_u32 s8, s8, 0x80
	s_addc_u32 s9, s9, 0
	global_load_dword v216, v25, s[8:9]
	v_lshl_add_u64 v[240:241], v[140:141], 0, s[30:31]
	v_lshl_add_u64 v[240:241], s[26:27], 0, v[240:241]
	v_add_co_u32_e64 v240, s[72:73], s90, v240
	s_nop 1
	v_addc_co_u32_e64 v241, s[72:73], 0, v241, s[72:73]
	global_load_dwordx2 v[218:219], v[240:241], off
	global_load_dwordx2 v[220:221], v[240:241], off offset:1024
	v_lshl_add_u64 v[240:241], v[150:151], 0, s[30:31]
	v_lshl_add_u64 v[240:241], s[26:27], 0, v[240:241]
	global_load_ushort v222, v[240:241], off offset:-32
	global_load_ushort v223, v[240:241], off offset:-28
	global_load_ushort v224, v[240:241], off offset:-24
	global_load_ushort v225, v[240:241], off offset:-20
	global_load_ushort v226, v[240:241], off offset:-16
	global_load_ushort v227, v[240:241], off offset:-12
	global_load_ushort v228, v[240:241], off offset:-8
	global_load_ushort v229, v[240:241], off offset:-4
	global_load_ushort v230, v[240:241], off
	global_load_ushort v231, v[240:241], off offset:4
	global_load_ushort v232, v[240:241], off offset:8
	global_load_ushort v233, v[240:241], off offset:12
	global_load_ushort v234, v[240:241], off offset:16
	global_load_ushort v235, v[240:241], off offset:20
	global_load_ushort v236, v[240:241], off offset:24
	global_load_ushort v237, v[240:241], off offset:28
	v_lshl_add_u64 v[240:241], v[148:149], 0, s[30:31]
	v_lshl_add_u64 v[240:241], s[26:27], 0, v[240:241]
	global_load_ushort v238, v[240:241], off
.Lssd_b_nopf:
	v_lshlrev_b32_e32 v87, 16, v87
	v_mul_f32_e32 v164, v91, v87
	v_pk_mul_f32 v[168:169], v[164:165], v[154:155] op_sel_hi:[0,1]
	v_pk_mul_f32 v[164:165], v[164:165], v[156:157] op_sel_hi:[0,1]
	v_lshlrev_b32_e32 v101, 16, v101
	v_pk_fma_f32 v[22:23], v[22:23], v[152:153], v[164:165] op_sel_hi:[1,0,1]
	v_mul_f32_e32 v164, v91, v101
	v_pk_fma_f32 v[20:21], v[20:21], v[152:153], v[168:169] op_sel_hi:[1,0,1]
	v_pk_mul_f32 v[168:169], v[164:165], v[154:155] op_sel_hi:[0,1]
	v_pk_mul_f32 v[164:165], v[164:165], v[156:157] op_sel_hi:[0,1]
	v_lshlrev_b32_e32 v105, 16, v105
	v_pk_fma_f32 v[2:3], v[2:3], v[152:153], v[164:165] op_sel_hi:[1,0,1]
	v_mul_f32_e32 v164, v91, v105
	v_pk_fma_f32 v[0:1], v[0:1], v[152:153], v[168:169] op_sel_hi:[1,0,1]
	v_pk_mul_f32 v[168:169], v[164:165], v[154:155] op_sel_hi:[0,1]
	v_pk_mul_f32 v[164:165], v[164:165], v[156:157] op_sel_hi:[0,1]
	v_lshlrev_b32_e32 v109, 16, v109
	v_pk_fma_f32 v[32:33], v[32:33], v[152:153], v[164:165] op_sel_hi:[1,0,1]
	v_mul_f32_e32 v164, v91, v109
	v_pk_fma_f32 v[30:31], v[30:31], v[152:153], v[168:169] op_sel_hi:[1,0,1]
	v_pk_mul_f32 v[168:169], v[164:165], v[154:155] op_sel_hi:[0,1]
	v_pk_mul_f32 v[164:165], v[164:165], v[156:157] op_sel_hi:[0,1]
	v_lshlrev_b32_e32 v113, 16, v113
	v_pk_fma_f32 v[6:7], v[6:7], v[152:153], v[164:165] op_sel_hi:[1,0,1]
	v_mul_f32_e32 v164, v91, v113
	v_pk_fma_f32 v[4:5], v[4:5], v[152:153], v[168:169] op_sel_hi:[1,0,1]
	v_pk_mul_f32 v[168:169], v[164:165], v[154:155] op_sel_hi:[0,1]
	v_pk_mul_f32 v[164:165], v[164:165], v[156:157] op_sel_hi:[0,1]
	v_lshlrev_b32_e32 v117, 16, v117
	v_pk_fma_f32 v[40:41], v[40:41], v[152:153], v[164:165] op_sel_hi:[1,0,1]
	v_mul_f32_e32 v164, v91, v117
	v_pk_fma_f32 v[38:39], v[38:39], v[152:153], v[168:169] op_sel_hi:[1,0,1]
	v_pk_mul_f32 v[168:169], v[164:165], v[154:155] op_sel_hi:[0,1]
	v_pk_mul_f32 v[164:165], v[164:165], v[156:157] op_sel_hi:[0,1]
	v_lshlrev_b32_e32 v121, 16, v121
	v_pk_fma_f32 v[10:11], v[10:11], v[152:153], v[164:165] op_sel_hi:[1,0,1]
	v_mul_f32_e32 v164, v91, v121
	v_pk_fma_f32 v[8:9], v[8:9], v[152:153], v[168:169] op_sel_hi:[1,0,1]
	v_pk_mul_f32 v[168:169], v[164:165], v[154:155] op_sel_hi:[0,1]
	v_pk_mul_f32 v[164:165], v[164:165], v[156:157] op_sel_hi:[0,1]
	v_lshlrev_b32_e32 v125, 16, v125
	v_pk_fma_f32 v[48:49], v[48:49], v[152:153], v[164:165] op_sel_hi:[1,0,1]
	v_mul_f32_e32 v164, v91, v125
	v_pk_fma_f32 v[46:47], v[46:47], v[152:153], v[168:169] op_sel_hi:[1,0,1]
	v_pk_mul_f32 v[168:169], v[164:165], v[154:155] op_sel_hi:[0,1]
	v_pk_mul_f32 v[164:165], v[164:165], v[156:157] op_sel_hi:[0,1]
	v_lshlrev_b32_e32 v129, 16, v129
	v_pk_fma_f32 v[18:19], v[18:19], v[152:153], v[164:165] op_sel_hi:[1,0,1]
	v_mul_f32_e32 v164, v91, v129
	v_pk_fma_f32 v[16:17], v[16:17], v[152:153], v[168:169] op_sel_hi:[1,0,1]
	v_pk_mul_f32 v[168:169], v[164:165], v[154:155] op_sel_hi:[0,1]
	v_pk_mul_f32 v[164:165], v[164:165], v[156:157] op_sel_hi:[0,1]
	v_lshlrev_b32_e32 v133, 16, v133
	v_pk_fma_f32 v[52:53], v[52:53], v[152:153], v[164:165] op_sel_hi:[1,0,1]
	v_mul_f32_e32 v164, v91, v133
	v_pk_fma_f32 v[50:51], v[50:51], v[152:153], v[168:169] op_sel_hi:[1,0,1]
; DI float bf2f(bf16_t b) { return __uint_as_float(((unsigned)b) << 16); }
; DI void ssd_scan(const Params& P, LAS unsigned char* lds) {
;     ...
;                   for (int i = 0; i < 16; ++i) { const int p = ph + 2 * (16 * half + i); const float xv = bf2f(XS[(size_t)row * 3072 + h * 64 + p]);
;                       S[i] = S[i] * dec + Bv * (dtv * xv);
;                       float yp = (S[i][0] * Cv[0] + S[i][1] * Cv[1]) + (S[i][2] * Cv[2] + S[i][3] * Cv[3]);
;                       yp += __shfl_xor(yp, 1); yp += __shfl_xor(yp, 2); yp += __shfl_xor(yp, 4); yp += __shfl_xor(yp, 8); yp += __shfl_xor(yp, 16);
;                       ysel = ((lane & 31) == i) ? yp : ysel; }
	v_pk_mul_f32 v[168:169], v[164:165], v[154:155] op_sel_hi:[0,1]
	v_pk_mul_f32 v[164:165], v[164:165], v[156:157] op_sel_hi:[0,1]
	v_lshlrev_b32_e32 v137, 16, v137
	v_pk_fma_f32 v[28:29], v[28:29], v[152:153], v[164:165] op_sel_hi:[1,0,1]
	v_mul_f32_e32 v164, v91, v137
	v_pk_fma_f32 v[26:27], v[26:27], v[152:153], v[168:169] op_sel_hi:[1,0,1]
	v_pk_mul_f32 v[168:169], v[164:165], v[154:155] op_sel_hi:[0,1]
	v_pk_mul_f32 v[164:165], v[164:165], v[156:157] op_sel_hi:[0,1]
	v_lshlrev_b32_e32 v147, 16, v147
	v_pk_fma_f32 v[56:57], v[56:57], v[152:153], v[164:165] op_sel_hi:[1,0,1]
	v_mul_f32_e32 v164, v91, v147
	v_pk_fma_f32 v[54:55], v[54:55], v[152:153], v[168:169] op_sel_hi:[1,0,1]
	v_pk_mul_f32 v[168:169], v[164:165], v[154:155] op_sel_hi:[0,1]
	v_pk_mul_f32 v[164:165], v[164:165], v[156:157] op_sel_hi:[0,1]
	v_pk_fma_f32 v[36:37], v[36:37], v[152:153], v[164:165] op_sel_hi:[1,0,1]
	v_mov_b32_e32 v165, v242
	v_pk_fma_f32 v[34:35], v[34:35], v[152:153], v[168:169] op_sel_hi:[1,0,1]
	v_mul_f32_e32 v87, v21, v99
	v_mul_f32_e32 v101, v1, v99
	v_mul_f32_e32 v105, v31, v99
	v_mul_f32_e32 v109, v5, v99
	v_mul_f32_e32 v113, v39, v99
	v_mul_f32_e32 v117, v9, v99
	v_mul_f32_e32 v121, v47, v99
	v_mul_f32_e32 v125, v17, v99
	v_mul_f32_e32 v129, v51, v99
	v_mul_f32_e32 v133, v27, v99
	v_mul_f32_e32 v137, v55, v99
	v_mul_f32_e32 v147, v35, v99
	v_fmac_f32_e32 v87, v20, v95
	v_mul_f32_e32 v89, v23, v97
	v_fmac_f32_e32 v101, v0, v95
	v_mul_f32_e32 v103, v3, v97
	v_fmac_f32_e32 v105, v30, v95
	v_mul_f32_e32 v107, v33, v97
	v_fmac_f32_e32 v109, v4, v95
	v_mul_f32_e32 v111, v7, v97
	v_fmac_f32_e32 v113, v38, v95
	v_mul_f32_e32 v115, v41, v97
	v_fmac_f32_e32 v117, v8, v95
	v_mul_f32_e32 v119, v11, v97
	v_fmac_f32_e32 v121, v46, v95
	v_mul_f32_e32 v123, v49, v97
	v_fmac_f32_e32 v125, v16, v95
	v_mul_f32_e32 v127, v19, v97
	v_fmac_f32_e32 v129, v50, v95
	v_mul_f32_e32 v131, v53, v97
	v_fmac_f32_e32 v133, v26, v95
	v_mul_f32_e32 v135, v29, v97
	v_fmac_f32_e32 v137, v54, v95
	v_mul_f32_e32 v139, v57, v97
	v_fmac_f32_e32 v147, v34, v95
	v_mul_f32_e32 v164, v37, v97
	v_fmac_f32_e32 v89, v22, v93
	v_fmac_f32_e32 v103, v2, v93
	v_fmac_f32_e32 v107, v32, v93
	v_fmac_f32_e32 v111, v6, v93
	v_fmac_f32_e32 v115, v40, v93
	v_fmac_f32_e32 v119, v10, v93
	v_fmac_f32_e32 v123, v48, v93
	v_fmac_f32_e32 v127, v18, v93
	v_fmac_f32_e32 v131, v52, v93
	v_fmac_f32_e32 v135, v28, v93
	v_fmac_f32_e32 v139, v56, v93
	v_fmac_f32_e32 v164, v36, v93
	v_add_f32_e32 v87, v87, v89
	v_add_f32_e32 v101, v101, v103
	v_add_f32_e32 v105, v105, v107
	v_add_f32_e32 v109, v109, v111
	v_add_f32_e32 v113, v113, v115
	v_add_f32_e32 v117, v117, v119
	v_add_f32_e32 v121, v121, v123
	v_add_f32_e32 v125, v125, v127
	v_add_f32_e32 v129, v129, v131
	v_add_f32_e32 v133, v133, v135
	v_add_f32_e32 v137, v137, v139
	v_add_f32_e32 v147, v147, v164
	ds_bpermute_b32 v89, v67, v87
	ds_bpermute_b32 v103, v67, v101
	ds_bpermute_b32 v107, v67, v105
	ds_bpermute_b32 v111, v67, v109
	ds_bpermute_b32 v115, v67, v113
	ds_bpermute_b32 v119, v67, v117
	ds_bpermute_b32 v123, v67, v121
	ds_bpermute_b32 v127, v67, v125
	ds_bpermute_b32 v131, v67, v129
	ds_bpermute_b32 v135, v67, v133
	ds_bpermute_b32 v139, v67, v137
	ds_bpermute_b32 v164, v67, v147
	s_waitcnt lgkmcnt(11)
	v_add_f32_e32 v87, v87, v89
	s_waitcnt lgkmcnt(10)
	v_add_f32_e32 v101, v101, v103
	s_waitcnt lgkmcnt(9)
	v_add_f32_e32 v105, v105, v107
	s_waitcnt lgkmcnt(8)
	v_add_f32_e32 v109, v109, v111
	s_waitcnt lgkmcnt(7)
	v_add_f32_e32 v113, v113, v115
	s_waitcnt lgkmcnt(6)
	v_add_f32_e32 v117, v117, v119
	v_lshlrev_b32_e32 v165, 16, v165
	v_mul_f32_e32 v166, v91, v165
	v_pk_mul_f32 v[168:169], v[166:167], v[154:155] op_sel_hi:[0,1]
	v_pk_fma_f32 v[58:59], v[58:59], v[152:153], v[168:169] op_sel_hi:[1,0,1]
	v_mov_b32_e32 v168, v243
	v_pk_mul_f32 v[170:171], v[166:167], v[156:157] op_sel_hi:[0,1]
	v_pk_fma_f32 v[60:61], v[60:61], v[152:153], v[170:171] op_sel_hi:[1,0,1]
	v_mul_f32_e32 v165, v59, v99
	v_fmac_f32_e32 v165, v58, v95
	v_mul_f32_e32 v166, v61, v97
	v_fmac_f32_e32 v166, v60, v93
	v_add_f32_e32 v165, v165, v166
	ds_bpermute_b32 v166, v67, v165
	s_waitcnt lgkmcnt(6)
	v_add_f32_e32 v121, v121, v123
	s_waitcnt lgkmcnt(5)
	v_add_f32_e32 v125, v125, v127
	s_waitcnt lgkmcnt(4)
	v_add_f32_e32 v129, v129, v131
	s_waitcnt lgkmcnt(3)
	v_add_f32_e32 v133, v133, v135
	s_waitcnt lgkmcnt(2)
	v_add_f32_e32 v137, v137, v139
	s_waitcnt lgkmcnt(1)
	v_add_f32_e32 v147, v147, v164
	s_waitcnt lgkmcnt(0)
	v_add_f32_e32 v165, v165, v166
	ds_bpermute_b32 v89, v75, v87
	ds_bpermute_b32 v103, v75, v101
	ds_bpermute_b32 v107, v75, v105
	ds_bpermute_b32 v111, v75, v109
	ds_bpermute_b32 v115, v75, v113
	ds_bpermute_b32 v119, v75, v117
	ds_bpermute_b32 v123, v75, v121
	ds_bpermute_b32 v127, v75, v125
	ds_bpermute_b32 v131, v75, v129
	ds_bpermute_b32 v135, v75, v133
	ds_bpermute_b32 v139, v75, v137
	ds_bpermute_b32 v164, v75, v147
	ds_bpermute_b32 v166, v75, v165
	s_waitcnt lgkmcnt(12)
	v_add_f32_e32 v87, v87, v89
	s_waitcnt lgkmcnt(11)
	v_add_f32_e32 v101, v101, v103
	s_waitcnt lgkmcnt(10)
	v_add_f32_e32 v105, v105, v107
	s_waitcnt lgkmcnt(9)
	v_add_f32_e32 v109, v109, v111
	s_waitcnt lgkmcnt(8)
	v_add_f32_e32 v113, v113, v115
	s_waitcnt lgkmcnt(7)
	v_add_f32_e32 v117, v117, v119
	s_waitcnt lgkmcnt(6)
	v_add_f32_e32 v121, v121, v123
	s_waitcnt lgkmcnt(5)
	v_add_f32_e32 v125, v125, v127
	s_waitcnt lgkmcnt(4)
	v_add_f32_e32 v129, v129, v131
	s_waitcnt lgkmcnt(3)
	v_add_f32_e32 v133, v133, v135
	s_waitcnt lgkmcnt(2)
	v_add_f32_e32 v137, v137, v139
	s_waitcnt lgkmcnt(1)
	v_add_f32_e32 v147, v147, v164
	s_waitcnt lgkmcnt(0)
; DI float bf2f(bf16_t b) { return __uint_as_float(((unsigned)b) << 16); }
; DI bf16_t f2bf(float f) { return (bf16_t)(pk2(f, 0.f) & 0xffffu); }
; DI void ssd_scan(const Params& P, LAS unsigned char* lds) {
;     ...
;                       float yp = (S[i][0] * Cv[0] + S[i][1] * Cv[1]) + (S[i][2] * Cv[2] + S[i][3] * Cv[3]);
;                       yp += __shfl_xor(yp, 1); yp += __shfl_xor(yp, 2); yp += __shfl_xor(yp, 4); yp += __shfl_xor(yp, 8); yp += __shfl_xor(yp, 16);
;                       ysel = ((lane & 31) == i) ? yp : ysel; }
;                   if ((lane & 31) < 16) { const int p = ph + 2 * (16 * half + (lane & 31)); const float xv = bf2f(XS[(size_t)row * 3072 + h * 64 + p]);
;                       YB[(size_t)row * 2048 + h * 64 + p] = f2bf(ysel + dsk * xv); } }
	v_add_f32_e32 v165, v165, v166
	ds_bpermute_b32 v89, v153, v87
	ds_bpermute_b32 v103, v153, v101
	ds_bpermute_b32 v107, v153, v105
	ds_bpermute_b32 v111, v153, v109
	ds_bpermute_b32 v115, v153, v113
	ds_bpermute_b32 v119, v153, v117
	ds_bpermute_b32 v123, v153, v121
	ds_bpermute_b32 v127, v153, v125
	ds_bpermute_b32 v131, v153, v129
	ds_bpermute_b32 v135, v153, v133
	ds_bpermute_b32 v139, v153, v137
	ds_bpermute_b32 v164, v153, v147
	ds_bpermute_b32 v166, v153, v165
	s_waitcnt lgkmcnt(12)
	v_add_f32_e32 v87, v87, v89
	s_waitcnt lgkmcnt(11)
	v_add_f32_e32 v101, v101, v103
	s_waitcnt lgkmcnt(10)
	v_add_f32_e32 v105, v105, v107
	s_waitcnt lgkmcnt(9)
	v_add_f32_e32 v109, v109, v111
	s_waitcnt lgkmcnt(8)
	v_add_f32_e32 v113, v113, v115
	s_waitcnt lgkmcnt(7)
	v_add_f32_e32 v117, v117, v119
	s_waitcnt lgkmcnt(6)
	v_add_f32_e32 v121, v121, v123
	s_waitcnt lgkmcnt(5)
	v_add_f32_e32 v125, v125, v127
	s_waitcnt lgkmcnt(4)
	v_add_f32_e32 v129, v129, v131
	s_waitcnt lgkmcnt(3)
	v_add_f32_e32 v133, v133, v135
	s_waitcnt lgkmcnt(2)
	v_add_f32_e32 v137, v137, v139
	s_waitcnt lgkmcnt(1)
	v_add_f32_e32 v147, v147, v164
	s_waitcnt lgkmcnt(0)
	v_add_f32_e32 v165, v165, v166
	ds_bpermute_b32 v89, v160, v87
	ds_bpermute_b32 v103, v160, v101
	ds_bpermute_b32 v107, v160, v105
	ds_bpermute_b32 v111, v160, v109
	ds_bpermute_b32 v115, v160, v113
	ds_bpermute_b32 v119, v160, v117
	ds_bpermute_b32 v123, v160, v121
	ds_bpermute_b32 v127, v160, v125
	ds_bpermute_b32 v131, v160, v129
	ds_bpermute_b32 v135, v160, v133
	ds_bpermute_b32 v139, v160, v137
	ds_bpermute_b32 v164, v160, v147
	v_lshlrev_b32_e32 v168, 16, v168
	v_mul_f32_e32 v168, v91, v168
	v_pk_mul_f32 v[170:171], v[168:169], v[154:155] op_sel_hi:[0,1]
	v_pk_fma_f32 v[42:43], v[42:43], v[152:153], v[170:171] op_sel_hi:[1,0,1]
	v_mov_b32_e32 v170, v244
	v_pk_mul_f32 v[168:169], v[168:169], v[156:157] op_sel_hi:[0,1]
	v_mov_b32_e32 v158, v245
	v_pk_fma_f32 v[44:45], v[44:45], v[152:153], v[168:169] op_sel_hi:[1,0,1]
	v_mul_f32_e32 v168, v43, v99
	v_fmac_f32_e32 v168, v42, v95
	v_mul_f32_e32 v169, v45, v97
	v_fmac_f32_e32 v169, v44, v93
	v_add_f32_e32 v168, v168, v169
	ds_bpermute_b32 v169, v67, v168
	ds_bpermute_b32 v166, v160, v165
	s_waitcnt lgkmcnt(13)
	v_add_f32_e32 v87, v87, v89
	s_waitcnt lgkmcnt(12)
	v_add_f32_e32 v101, v101, v103
	s_waitcnt lgkmcnt(11)
	v_add_f32_e32 v105, v105, v107
	s_waitcnt lgkmcnt(1)
	v_add_f32_e32 v168, v168, v169
	ds_bpermute_b32 v169, v75, v168
	v_add_f32_e32 v109, v109, v111
	v_add_f32_e32 v113, v113, v115
	v_add_f32_e32 v117, v117, v119
	v_add_f32_e32 v121, v121, v123
	s_waitcnt lgkmcnt(0)
	v_add_f32_e32 v168, v168, v169
	ds_bpermute_b32 v169, v153, v168
	v_add_f32_e32 v125, v125, v127
	v_add_f32_e32 v129, v129, v131
	v_add_f32_e32 v133, v133, v135
	v_add_f32_e32 v137, v137, v139
	s_waitcnt lgkmcnt(0)
	v_add_f32_e32 v168, v168, v169
	ds_bpermute_b32 v169, v160, v168
	v_add_f32_e32 v147, v147, v164
	v_add_f32_e32 v165, v165, v166
	ds_bpermute_b32 v89, v161, v87
	ds_bpermute_b32 v103, v161, v101
	s_waitcnt lgkmcnt(2)
	v_add_f32_e32 v168, v168, v169
	ds_bpermute_b32 v107, v161, v105
	ds_bpermute_b32 v111, v161, v109
	ds_bpermute_b32 v115, v161, v113
	ds_bpermute_b32 v119, v161, v117
	ds_bpermute_b32 v123, v161, v121
	ds_bpermute_b32 v127, v161, v125
	ds_bpermute_b32 v131, v161, v129
	ds_bpermute_b32 v135, v161, v133
	ds_bpermute_b32 v139, v161, v137
	ds_bpermute_b32 v164, v161, v147
	ds_bpermute_b32 v166, v161, v165
	ds_bpermute_b32 v169, v161, v168
	v_lshlrev_b32_e32 v170, 16, v170
	v_mul_f32_e32 v170, v91, v170
	v_lshlrev_b32_e32 v158, 16, v158
	v_mul_f32_e32 v158, v91, v158
	v_pk_mul_f32 v[172:173], v[170:171], v[154:155] op_sel_hi:[0,1]
	v_pk_mul_f32 v[154:155], v[158:159], v[154:155] op_sel_hi:[0,1]
	v_pk_mul_f32 v[170:171], v[170:171], v[156:157] op_sel_hi:[0,1]
	v_pk_fma_f32 v[62:63], v[62:63], v[152:153], v[172:173] op_sel_hi:[1,0,1]
	v_pk_mul_f32 v[156:157], v[158:159], v[156:157] op_sel_hi:[0,1]
	v_pk_fma_f32 v[12:13], v[12:13], v[152:153], v[154:155] op_sel_hi:[1,0,1]
	v_pk_fma_f32 v[64:65], v[64:65], v[152:153], v[170:171] op_sel_hi:[1,0,1]
	v_mul_f32_e32 v170, v63, v99
	v_pk_fma_f32 v[14:15], v[14:15], v[152:153], v[156:157] op_sel_hi:[1,0,1]
	v_mul_f32_e32 v91, v13, v99
	v_fmac_f32_e32 v170, v62, v95
	v_mul_f32_e32 v171, v65, v97
	v_fmac_f32_e32 v91, v12, v95
	v_mul_f32_e32 v95, v15, v97
	v_fmac_f32_e32 v171, v64, v93
	v_fmac_f32_e32 v95, v14, v93
	v_add_f32_e32 v170, v170, v171
	v_add_f32_e32 v91, v91, v95
	ds_bpermute_b32 v171, v67, v170
	ds_bpermute_b32 v93, v67, v91
	s_waitcnt lgkmcnt(1)
	v_add_f32_e32 v170, v170, v171
	s_waitcnt lgkmcnt(0)
	v_add_f32_e32 v91, v91, v93
	ds_bpermute_b32 v171, v75, v170
	ds_bpermute_b32 v93, v75, v91
	s_waitcnt lgkmcnt(1)
	v_add_f32_e32 v170, v170, v171
	s_waitcnt lgkmcnt(0)
	v_add_f32_e32 v91, v91, v93
	ds_bpermute_b32 v171, v153, v170
	ds_bpermute_b32 v93, v153, v91
	s_waitcnt lgkmcnt(1)
	v_add_f32_e32 v170, v170, v171
	s_waitcnt lgkmcnt(0)
	v_add_f32_e32 v91, v91, v93
	ds_bpermute_b32 v171, v160, v170
	ds_bpermute_b32 v93, v160, v91
	s_waitcnt lgkmcnt(1)
	v_add_f32_e32 v170, v170, v171
	s_waitcnt lgkmcnt(0)
	v_add_f32_e32 v91, v91, v93
	ds_bpermute_b32 v171, v161, v170
	ds_bpermute_b32 v93, v161, v91
	s_and_saveexec_b64 s[8:9], vcc
	s_cbranch_execz .LBB0_191
	v_lshl_add_u64 v[154:155], s[26:27], 0, v[148:149]
	v_add_f32_e32 v87, v87, v89
	v_mov_b32_e32 v89, v239
	v_add_f32_e32 v101, v101, v103
	v_cndmask_b32_e64 v87, 0, v87, s[38:39]
	v_add_f32_e32 v105, v105, v107
	v_cndmask_b32_e64 v87, v87, v101, s[40:41]
	v_add_f32_e32 v109, v109, v111
	v_cndmask_b32_e64 v87, v87, v105, s[42:43]
	v_add_f32_e32 v113, v113, v115
	v_cndmask_b32_e64 v87, v87, v109, s[44:45]
	v_add_f32_e32 v117, v117, v119
	v_cndmask_b32_e64 v87, v87, v113, s[46:47]
	v_add_f32_e32 v121, v121, v123
	v_cndmask_b32_e64 v87, v87, v117, s[48:49]
	v_add_f32_e32 v125, v125, v127
	v_cndmask_b32_e64 v87, v87, v121, s[50:51]
	v_add_f32_e32 v129, v129, v131
	v_cndmask_b32_e64 v87, v87, v125, s[52:53]
	v_add_f32_e32 v133, v133, v135
	v_cndmask_b32_e64 v87, v87, v129, s[54:55]
	v_add_f32_e32 v137, v137, v139
	v_cndmask_b32_e64 v87, v87, v133, s[56:57]
	v_add_f32_e32 v99, v147, v164
	v_cndmask_b32_e64 v87, v87, v137, s[58:59]
	v_add_f32_e32 v97, v165, v166
	v_cndmask_b32_e64 v87, v87, v99, s[60:61]
	v_add_f32_e32 v95, v168, v169
	v_cndmask_b32_e64 v87, v87, v97, s[62:63]
	s_waitcnt lgkmcnt(0)
	v_add_f32_e32 v91, v91, v93
	v_add_f32_e32 v93, v170, v171
	v_cndmask_b32_e64 v87, v87, v95, s[64:65]
	v_cndmask_b32_e64 v87, v87, v93, s[66:67]
	v_cndmask_b32_e64 v87, v87, v91, s[68:69]
	v_lshl_add_u64 v[154:155], s[26:27], 0, v[142:143]
	v_lshlrev_b32_e32 v89, 16, v89
	v_fmac_f32_e32 v87, v163, v89
	v_cvt_pk_bf16_f32 v87, v87, s0
	global_store_short v[154:155], v87, off
	s_branch .LBB0_191
